# S4 prologue: counted wait (vmcnt(8)) instead of vmcnt(0) before the rstd table reduce
# speedup vs baseline: 1.0018x; 1.0018x over previous
.LBB0_985:
	v_readlane_b32 s34, v246, 2
	v_readlane_b32 s35, v246, 3
	s_add_u32 s26, s34, 0xf800000
	s_mov_b64 s[28:29], 0x80
	s_addc_u32 s27, s35, 0
	s_and_b32 s4, s3, 3
	s_add_i32 m0, s54, 0x18000
	v_lshl_add_u64 v[8:9], v[8:9], 0, s[28:29]
	s_lshl_b32 s58, s33, 1
	s_lshl_b32 s5, s1, 13
	s_lshl_b32 s7, s4, 12
	s_and_b32 s59, s2, -2
	s_waitcnt vmcnt(2)
	s_barrier
	global_load_lds_dwordx4 v[8:9], off
	v_lshl_add_u64 v[6:7], v[6:7], 0, s[28:29]
	s_add_i32 m0, s54, 0x1a000
	s_add_i32 s60, s54, 0x8000
	s_add_i32 s61, s54, 0xa000
	global_load_lds_dwordx4 v[6:7], off
	v_lshl_add_u64 v[2:3], v[2:3], 0, s[28:29]
	s_mov_b32 m0, s60
	s_add_u32 s2, s10, 0x40080
	global_load_lds_dwordx4 v[2:3], off
	v_lshl_add_u64 v[2:3], v[4:5], 0, s[28:29]
	s_mov_b32 m0, s61
	s_addc_u32 s3, s11, 0
	global_load_lds_dwordx4 v[2:3], off
	s_add_i32 m0, s54, 0x1c000
	v_lshl_add_u64 v[2:3], s[2:3], 0, v[184:185]
	global_load_lds_dwordx4 v[2:3], off
	v_lshl_add_u64 v[2:3], s[2:3], 0, v[188:189]
	s_add_i32 m0, s54, 0x1e000
	v_and_b32_e32 v179, 15, v0
	global_load_lds_dwordx4 v[2:3], off
	v_bfe_u32 v2, v0, 4, 2
	v_lshl_or_b32 v212, s1, 6, v179
	v_lshlrev_b32_e32 v3, 3, v2
	v_lshlrev_b32_e32 v2, 4, v2
	v_lshlrev_b32_e32 v6, 6, v0
	s_movk_i32 s1, 0x3c0
	s_cmpk_lt_u32 s0, 0x100
	v_and_or_b32 v6, v6, s1, v2
	s_cselect_b64 s[30:31], -1, 0
	s_and_b32 s0, s0, 0xffffff00
	s_lshl_b32 s1, s4, 6
	v_lshl_or_b32 v214, s4, 5, v3
	s_or_b32 s0, s1, s0
	v_mov_b32_e32 v3, v185
	v_lshl_or_b32 v4, v179, 6, v2
	v_or3_b32 v215, s0, v2, v179
	v_lshl_add_u64 v[2:3], s[34:35], 0, v[2:3]
	s_mov_b64 s[0:1], 0x1bb00000
	v_lshl_add_u64 v[190:191], v[2:3], 0, s[0:1]
	v_lshlrev_b32_e32 v2, 8, v0
	v_and_b32_e32 v2, 0x18000, v2
	v_lshlrev_b32_e32 v3, 11, v12
	v_or3_b32 v2, v10, v2, v3
	v_add_u32_e32 v192, v2, v11
	v_lshlrev_b32_e32 v2, 4, v13
	v_and_b32_e32 v2, 0x38000, v2
	v_and_b32_e32 v5, 32, v180
	s_waitcnt vmcnt(6)
	s_add_u32 s34, s34, 0x3e40
	v_or3_b32 v2, v10, v2, v3
	v_bitop3_b32 v4, v4, s5, v5 bitop3:0xde
	v_bitop3_b32 v213, s7, v6, v5 bitop3:0xf6
	s_addc_u32 s35, s35, 0
	v_add_u32_e32 v194, v2, v11
	s_add_i32 s62, 0, 0x10000
	s_add_i32 s63, 0, 0x14000
	v_mbcnt_lo_u32_b32 v2, -1, 0
	v_lshrrev_b32_e32 v1, 4, v0
	v_add_u32_e32 v216, 0x200, v215
	v_add_u32_e32 v217, 0x400, v215
	v_add_u32_e32 v218, 0x600, v215
	v_mov_b32_e32 v193, v185
	v_mov_b32_e32 v195, v185
	v_add_u32_e32 v219, s62, v213
	v_add_u32_e32 v220, s63, v213
	v_add_u32_e32 v221, 0, v4
	s_movk_i32 s64, 0x80
	s_movk_i32 s65, 0x1550
	s_movk_i32 s66, 0x154f
	s_movk_i32 s67, 0xfb10
	v_mbcnt_hi_u32_b32 v181, -1, v2
	v_mov_b32_e32 v222, 0x358637bd
	s_movk_i32 s68, 0x1600
	s_mov_b32 s69, 0x34a0000
	s_add_i32 s70, 0, 0x201ac
	s_mov_b32 s0, s52
	s_mov_b32 s72, 0
	s_waitcnt vmcnt(8)
	v_add_f32_e32 v114, v114, v115
	v_add_f32_e32 v116, v116, v117
	v_add_f32_e32 v118, v118, v119
	v_add_f32_e32 v120, v120, v121
	v_add_f32_e32 v122, v122, v123
	v_add_f32_e32 v124, v124, v125
	v_add_f32_e32 v126, v126, v127
	v_add_f32_e32 v128, v128, v129
	v_add_f32_e32 v114, v114, v116
	v_add_f32_e32 v118, v118, v120
	v_add_f32_e32 v122, v122, v124
	v_add_f32_e32 v126, v126, v128
	v_add_f32_e32 v114, v114, v118
	v_add_f32_e32 v122, v122, v126
	v_add_f32_e32 v114, v114, v122
	v_fmamk_f32 v114, v114, 0x3a800000, v222
	v_rsq_f32_e32 v114, v114
	v_mov_b32_e32 v131, 0x21000
	v_lshl_add_u32 v131, v0, 2, v131
	ds_write_b32 v131, v114
	s_waitcnt lgkmcnt(0)
	s_barrier
	s_branch .LBB0_988
